# conv3+SiLU phases: column-strip mapping, causal halo rows carried in registers across row groups (Z reads 10->8 rows per 8), weights loaded once per thread
# speedup vs baseline: 1.0083x; 1.0080x over previous
.LBB0_893:
	s_cmp_lt_i32 s64, 10
	s_cselect_b64 s[4:5], -1, 0
	s_and_b64 s[0:1], s[4:5], s[2:3]
	s_andn2_b64 vcc, exec, s[0:1]
	s_cbranch_vccnz .LBB0_906
	s_lshl_b32 s8, s88, 9
	s_waitcnt vmcnt(0)
	v_or_b32_e32 v1, s8, v0
	s_mov_b32 s0, 0x158000
	v_cmp_gt_i32_e32 vcc, s0, v1
	s_and_saveexec_b64 s[6:7], vcc
	s_cbranch_execz .LBB0_905
	s_waitcnt vmcnt(0) lgkmcnt(0)
	v_lshrrev_b32_e32 v1, 6, v0
	v_lshlrev_b32_e32 v1, 14, v1
	v_and_b32_e32 v2, 63, v0
	v_lshl_or_b32 v1, v2, 4, v1
	ds_write_b128 v1, v[138:141]
	ds_write_b128 v1, v[142:145] offset:1024
	ds_write_b128 v1, v[146:149] offset:2048
	ds_write_b128 v1, v[150:153] offset:3072
	ds_write_b128 v1, v[154:157] offset:4096
	ds_write_b128 v1, v[158:161] offset:5120
	ds_write_b128 v1, v[162:165] offset:6144
	ds_write_b128 v1, v[166:169] offset:7168
	ds_write_b128 v1, v[170:173] offset:8192
	ds_write_b128 v1, v[174:177] offset:9216
	ds_write_b128 v1, v[178:181] offset:10240
	ds_write_b128 v1, v[182:185] offset:11264
	ds_write_b128 v1, v[186:189] offset:12288
	ds_write_b128 v1, v[190:193] offset:13312
	ds_write_b128 v1, v[194:197] offset:14336
	ds_write_b128 v1, v[198:201] offset:15360
	v_readlane_b32 s24, v247, 3
	v_readlane_b32 s25, v247, 4
	s_load_dwordx4 s[8:11], s[24:25], 0xd0
	s_waitcnt lgkmcnt(0)
	s_add_u32 s12, s10, 0x0
	s_addc_u32 s13, s11, 0
	s_add_u32 s14, s12, 0xac00
	s_addc_u32 s15, s13, 0
	s_add_u32 s8, s8, 0x0
	s_addc_u32 s9, s9, 0
	s_add_u32 s10, s8, 0xac00
	s_addc_u32 s11, s9, 0
	s_mov_b64 s[16:17], s[70:71]
	s_add_u32 s18, s70, 0x5600
	s_addc_u32 s19, s71, 0
	s_add_u32 s20, s94, 0x72500000
	s_addc_u32 s21, s95, 0
	s_mov_b32 s23, 0x56000
	s_mov_b32 s28, 0x2b000
	s_mov_b32 s22, 11
	s_lshl_b32 s24, s88, 9
	v_add_u32_e32 v1, s24, v0
	v_lshrrev_b32_e32 v175, 5, v1
	v_mov_b32_e32 v178, 0xbe83
	v_mul_lo_u32 v175, v175, v178
	v_lshrrev_b32_e32 v175, 21, v175
	v_mul_u32_u24_e32 v178, 0x560, v175
	v_sub_u32_e32 v170, v1, v178
	v_min_u32_e32 v175, 94, v175
	v_mul_u32_u24_e32 v175, 0xac7, v175
	v_lshrrev_b32_e32 v171, 8, v175
	v_lshlrev_b32_e32 v175, 4, v170
	v_mad_u32_u24 v172, v171, s23, v175
	v_mad_u32_u24 v173, v171, s28, v175
	v_lshlrev_b32_e32 v174, 5, v170
	v_add_u32_e32 v176, 0x15800, v174
	v_add_u32_e32 v177, 0x2b000, v174
	global_load_dwordx4 v[2:5], v174, s[8:9]
	global_load_dwordx4 v[6:9], v174, s[8:9] offset:16
	global_load_dwordx4 v[10:13], v176, s[8:9]
	global_load_dwordx4 v[14:17], v176, s[8:9] offset:16
	global_load_dwordx4 v[18:21], v177, s[8:9]
	global_load_dwordx4 v[22:25], v177, s[8:9] offset:16
	global_load_dwordx4 v[50:53], v174, s[12:13]
	global_load_dwordx4 v[54:57], v174, s[12:13] offset:16
	global_load_dwordx4 v[26:29], v174, s[10:11]
	global_load_dwordx4 v[30:33], v174, s[10:11] offset:16
	global_load_dwordx4 v[34:37], v176, s[10:11]
	global_load_dwordx4 v[38:41], v176, s[10:11] offset:16
	global_load_dwordx4 v[42:45], v177, s[10:11]
	global_load_dwordx4 v[46:49], v177, s[10:11] offset:16
	global_load_dwordx4 v[58:61], v174, s[14:15]
	global_load_dwordx4 v[62:65], v174, s[14:15] offset:16
	v_and_b32_e32 v175, 0xff, v171
	v_cmp_ne_u32_e32 vcc, 0, v175
	v_mov_b32_e32 v178, 0x15800
	s_nop 0
	v_cndmask_b32_e32 v175, 0, v178, vcc
	v_sub_u32_e32 v176, v172, v175
	v_lshrrev_b32_e32 v175, 1, v175
	v_sub_u32_e32 v177, v172, v175
	global_load_dwordx4 v[66:69], v176, s[16:17] nt
	global_load_dwordx4 v[70:73], v176, s[18:19] nt
	global_load_dwordx4 v[74:77], v177, s[16:17] nt
	global_load_dwordx4 v[78:81], v177, s[18:19] nt
	s_waitcnt vmcnt(0)
	v_lshlrev_b32_e32 v98, 16, v66
	v_and_b32_e32 v99, 0xffff0000, v66
	v_lshlrev_b32_e32 v100, 16, v67
	v_and_b32_e32 v101, 0xffff0000, v67
	v_lshlrev_b32_e32 v102, 16, v68
	v_and_b32_e32 v103, 0xffff0000, v68
	v_lshlrev_b32_e32 v104, 16, v69
	v_and_b32_e32 v105, 0xffff0000, v69
	v_lshlrev_b32_e32 v106, 16, v70
	v_and_b32_e32 v107, 0xffff0000, v70
	v_lshlrev_b32_e32 v108, 16, v71
	v_and_b32_e32 v109, 0xffff0000, v71
	v_lshlrev_b32_e32 v110, 16, v72
	v_and_b32_e32 v111, 0xffff0000, v72
	v_lshlrev_b32_e32 v112, 16, v73
	v_and_b32_e32 v113, 0xffff0000, v73
	v_lshlrev_b32_e32 v114, 16, v74
	v_and_b32_e32 v115, 0xffff0000, v74
	v_lshlrev_b32_e32 v116, 16, v75
	v_and_b32_e32 v117, 0xffff0000, v75
	v_lshlrev_b32_e32 v118, 16, v76
	v_and_b32_e32 v119, 0xffff0000, v76
	v_lshlrev_b32_e32 v120, 16, v77
	v_and_b32_e32 v121, 0xffff0000, v77
	v_lshlrev_b32_e32 v122, 16, v78
	v_and_b32_e32 v123, 0xffff0000, v78
	v_lshlrev_b32_e32 v124, 16, v79
	v_and_b32_e32 v125, 0xffff0000, v79
	v_lshlrev_b32_e32 v126, 16, v80
	v_and_b32_e32 v127, 0xffff0000, v80
	v_lshlrev_b32_e32 v128, 16, v81
	v_and_b32_e32 v129, 0xffff0000, v81
	global_load_dwordx4 v[66:69], v172, s[16:17] nt
	global_load_dwordx4 v[70:73], v172, s[18:19] nt
	v_add_u32_e32 v172, 0xac00, v172
	global_load_dwordx4 v[74:77], v172, s[16:17] nt
	global_load_dwordx4 v[78:81], v172, s[18:19] nt
	v_add_u32_e32 v172, 0xac00, v172
	global_load_dwordx4 v[82:85], v172, s[16:17] nt
	global_load_dwordx4 v[86:89], v172, s[18:19] nt
	v_add_u32_e32 v172, 0xac00, v172
	global_load_dwordx4 v[90:93], v172, s[16:17] nt
	global_load_dwordx4 v[94:97], v172, s[18:19] nt
	v_add_u32_e32 v172, 0xac00, v172
	s_waitcnt vmcnt(0)
.Lgrp_cw0:
	v_and_b32_e32 v175, 0xff, v171
	v_cmp_ne_u32_e64 s[24:25], 0, v175
	v_add_u32_e32 v171, 1, v171
	s_nop 3
	v_cndmask_b32_e64 v98, 0, v98, s[24:25]
	v_cndmask_b32_e64 v99, 0, v99, s[24:25]
	v_cndmask_b32_e64 v100, 0, v100, s[24:25]
	v_cndmask_b32_e64 v101, 0, v101, s[24:25]
	v_cndmask_b32_e64 v102, 0, v102, s[24:25]
	v_cndmask_b32_e64 v103, 0, v103, s[24:25]
	v_cndmask_b32_e64 v104, 0, v104, s[24:25]
	v_cndmask_b32_e64 v105, 0, v105, s[24:25]
	v_cndmask_b32_e64 v106, 0, v106, s[24:25]
	v_cndmask_b32_e64 v107, 0, v107, s[24:25]
	v_cndmask_b32_e64 v108, 0, v108, s[24:25]
	v_cndmask_b32_e64 v109, 0, v109, s[24:25]
	v_cndmask_b32_e64 v110, 0, v110, s[24:25]
	v_cndmask_b32_e64 v111, 0, v111, s[24:25]
	v_cndmask_b32_e64 v112, 0, v112, s[24:25]
	v_cndmask_b32_e64 v113, 0, v113, s[24:25]
	v_cndmask_b32_e64 v114, 0, v114, s[24:25]
	v_cndmask_b32_e64 v115, 0, v115, s[24:25]
	v_cndmask_b32_e64 v116, 0, v116, s[24:25]
	v_cndmask_b32_e64 v117, 0, v117, s[24:25]
	v_cndmask_b32_e64 v118, 0, v118, s[24:25]
	v_cndmask_b32_e64 v119, 0, v119, s[24:25]
	v_cndmask_b32_e64 v120, 0, v120, s[24:25]
	v_cndmask_b32_e64 v121, 0, v121, s[24:25]
	v_cndmask_b32_e64 v122, 0, v122, s[24:25]
	v_cndmask_b32_e64 v123, 0, v123, s[24:25]
	v_cndmask_b32_e64 v124, 0, v124, s[24:25]
	v_cndmask_b32_e64 v125, 0, v125, s[24:25]
	v_cndmask_b32_e64 v126, 0, v126, s[24:25]
	v_cndmask_b32_e64 v127, 0, v127, s[24:25]
	v_cndmask_b32_e64 v128, 0, v128, s[24:25]
	v_cndmask_b32_e64 v129, 0, v129, s[24:25]
	s_waitcnt vmcnt(10)
	v_lshlrev_b32_e32 v130, 16, v66
	v_and_b32_e32 v131, 0xffff0000, v66
	v_lshlrev_b32_e32 v132, 16, v67
	v_and_b32_e32 v133, 0xffff0000, v67
	v_lshlrev_b32_e32 v134, 16, v68
	v_and_b32_e32 v135, 0xffff0000, v68
	v_lshlrev_b32_e32 v136, 16, v69
	v_and_b32_e32 v137, 0xffff0000, v69
	v_lshlrev_b32_e32 v138, 16, v70
	v_and_b32_e32 v139, 0xffff0000, v70
	v_lshlrev_b32_e32 v140, 16, v71
	v_and_b32_e32 v141, 0xffff0000, v71
	v_lshlrev_b32_e32 v142, 16, v72
	v_and_b32_e32 v143, 0xffff0000, v72
	v_lshlrev_b32_e32 v144, 16, v73
	v_and_b32_e32 v145, 0xffff0000, v73
	global_load_dwordx4 v[66:69], v172, s[16:17] nt
	global_load_dwordx4 v[70:73], v172, s[18:19] nt
	v_add_u32_e32 v172, 0xac00, v172
	v_pk_fma_f32 v[146:147], v[2:3], v[98:99], v[50:51]
	v_pk_fma_f32 v[148:149], v[4:5], v[100:101], v[52:53]
	v_pk_fma_f32 v[150:151], v[6:7], v[102:103], v[54:55]
	v_pk_fma_f32 v[152:153], v[8:9], v[104:105], v[56:57]
	v_pk_fma_f32 v[154:155], v[26:27], v[106:107], v[58:59]
	v_pk_fma_f32 v[156:157], v[28:29], v[108:109], v[60:61]
	v_pk_fma_f32 v[158:159], v[30:31], v[110:111], v[62:63]
	v_pk_fma_f32 v[160:161], v[32:33], v[112:113], v[64:65]
	v_pk_fma_f32 v[146:147], v[10:11], v[114:115], v[146:147]
	v_pk_fma_f32 v[148:149], v[12:13], v[116:117], v[148:149]
	v_pk_fma_f32 v[150:151], v[14:15], v[118:119], v[150:151]
	v_pk_fma_f32 v[152:153], v[16:17], v[120:121], v[152:153]
	v_pk_fma_f32 v[154:155], v[34:35], v[122:123], v[154:155]
	v_pk_fma_f32 v[156:157], v[36:37], v[124:125], v[156:157]
	v_pk_fma_f32 v[158:159], v[38:39], v[126:127], v[158:159]
	v_pk_fma_f32 v[160:161], v[40:41], v[128:129], v[160:161]
	v_pk_fma_f32 v[146:147], v[18:19], v[130:131], v[146:147]
	v_pk_fma_f32 v[148:149], v[20:21], v[132:133], v[148:149]
	v_pk_fma_f32 v[150:151], v[22:23], v[134:135], v[150:151]
	v_pk_fma_f32 v[152:153], v[24:25], v[136:137], v[152:153]
	v_pk_fma_f32 v[154:155], v[42:43], v[138:139], v[154:155]
	v_pk_fma_f32 v[156:157], v[44:45], v[140:141], v[156:157]
	v_pk_fma_f32 v[158:159], v[46:47], v[142:143], v[158:159]
	v_pk_fma_f32 v[160:161], v[48:49], v[144:145], v[160:161]
	v_mul_f32_e32 v162, 0xbfb8aa3b, v146
	v_mul_f32_e32 v163, 0xbfb8aa3b, v147
	v_mul_f32_e32 v164, 0xbfb8aa3b, v148
	v_mul_f32_e32 v165, 0xbfb8aa3b, v149
	v_mul_f32_e32 v166, 0xbfb8aa3b, v150
	v_mul_f32_e32 v167, 0xbfb8aa3b, v151
	v_mul_f32_e32 v168, 0xbfb8aa3b, v152
	v_mul_f32_e32 v169, 0xbfb8aa3b, v153
	v_exp_f32_e32 v162, v162
	v_exp_f32_e32 v163, v163
	v_exp_f32_e32 v164, v164
	v_exp_f32_e32 v165, v165
	v_exp_f32_e32 v166, v166
	v_exp_f32_e32 v167, v167
	v_exp_f32_e32 v168, v168
	v_exp_f32_e32 v169, v169
	v_add_f32_e32 v162, 1.0, v162
	v_add_f32_e32 v163, 1.0, v163
	v_add_f32_e32 v164, 1.0, v164
	v_add_f32_e32 v165, 1.0, v165
	v_add_f32_e32 v166, 1.0, v166
	v_add_f32_e32 v167, 1.0, v167
	v_add_f32_e32 v168, 1.0, v168
	v_add_f32_e32 v169, 1.0, v169
	v_rcp_f32_e32 v162, v162
	v_rcp_f32_e32 v163, v163
	v_rcp_f32_e32 v164, v164
	v_rcp_f32_e32 v165, v165
	v_rcp_f32_e32 v166, v166
	v_rcp_f32_e32 v167, v167
	v_rcp_f32_e32 v168, v168
	v_rcp_f32_e32 v169, v169
	s_nop 0
	v_pk_mul_f32 v[146:147], v[146:147], v[162:163]
	v_pk_mul_f32 v[148:149], v[148:149], v[164:165]
	v_pk_mul_f32 v[150:151], v[150:151], v[166:167]
	v_pk_mul_f32 v[152:153], v[152:153], v[168:169]
	v_pk_mul_f32 v[146:147], v[154:155], v[146:147]
	v_pk_mul_f32 v[148:149], v[156:157], v[148:149]
	v_pk_mul_f32 v[150:151], v[158:159], v[150:151]
	v_pk_mul_f32 v[152:153], v[160:161], v[152:153]
	v_cvt_pk_bf16_f32 v162, v146, v147
	v_cvt_pk_bf16_f32 v163, v148, v149
	v_cvt_pk_bf16_f32 v164, v150, v151
	v_cvt_pk_bf16_f32 v165, v152, v153
	global_store_dwordx4 v173, v[162:165], s[20:21]
	v_add_u32_e32 v173, 0x5600, v173
	s_waitcnt vmcnt(10)
	v_lshlrev_b32_e32 v98, 16, v74
	v_and_b32_e32 v99, 0xffff0000, v74
	v_lshlrev_b32_e32 v100, 16, v75
	v_and_b32_e32 v101, 0xffff0000, v75
	v_lshlrev_b32_e32 v102, 16, v76
	v_and_b32_e32 v103, 0xffff0000, v76
	v_lshlrev_b32_e32 v104, 16, v77
	v_and_b32_e32 v105, 0xffff0000, v77
	v_lshlrev_b32_e32 v106, 16, v78
	v_and_b32_e32 v107, 0xffff0000, v78
	v_lshlrev_b32_e32 v108, 16, v79
	v_and_b32_e32 v109, 0xffff0000, v79
	v_lshlrev_b32_e32 v110, 16, v80
	v_and_b32_e32 v111, 0xffff0000, v80
	v_lshlrev_b32_e32 v112, 16, v81
	v_and_b32_e32 v113, 0xffff0000, v81
	global_load_dwordx4 v[74:77], v172, s[16:17] nt
	global_load_dwordx4 v[78:81], v172, s[18:19] nt
	v_add_u32_e32 v172, 0xac00, v172
	v_pk_fma_f32 v[146:147], v[2:3], v[114:115], v[50:51]
	v_pk_fma_f32 v[148:149], v[4:5], v[116:117], v[52:53]
	v_pk_fma_f32 v[150:151], v[6:7], v[118:119], v[54:55]
	v_pk_fma_f32 v[152:153], v[8:9], v[120:121], v[56:57]
	v_pk_fma_f32 v[154:155], v[26:27], v[122:123], v[58:59]
	v_pk_fma_f32 v[156:157], v[28:29], v[124:125], v[60:61]
	v_pk_fma_f32 v[158:159], v[30:31], v[126:127], v[62:63]
	v_pk_fma_f32 v[160:161], v[32:33], v[128:129], v[64:65]
	v_pk_fma_f32 v[146:147], v[10:11], v[130:131], v[146:147]
	v_pk_fma_f32 v[148:149], v[12:13], v[132:133], v[148:149]
	v_pk_fma_f32 v[150:151], v[14:15], v[134:135], v[150:151]
	v_pk_fma_f32 v[152:153], v[16:17], v[136:137], v[152:153]
	v_pk_fma_f32 v[154:155], v[34:35], v[138:139], v[154:155]
	v_pk_fma_f32 v[156:157], v[36:37], v[140:141], v[156:157]
	v_pk_fma_f32 v[158:159], v[38:39], v[142:143], v[158:159]
	v_pk_fma_f32 v[160:161], v[40:41], v[144:145], v[160:161]
	v_pk_fma_f32 v[146:147], v[18:19], v[98:99], v[146:147]
	v_pk_fma_f32 v[148:149], v[20:21], v[100:101], v[148:149]
	v_pk_fma_f32 v[150:151], v[22:23], v[102:103], v[150:151]
	v_pk_fma_f32 v[152:153], v[24:25], v[104:105], v[152:153]
	v_pk_fma_f32 v[154:155], v[42:43], v[106:107], v[154:155]
	v_pk_fma_f32 v[156:157], v[44:45], v[108:109], v[156:157]
	v_pk_fma_f32 v[158:159], v[46:47], v[110:111], v[158:159]
	v_pk_fma_f32 v[160:161], v[48:49], v[112:113], v[160:161]
	v_mul_f32_e32 v162, 0xbfb8aa3b, v146
	v_mul_f32_e32 v163, 0xbfb8aa3b, v147
	v_mul_f32_e32 v164, 0xbfb8aa3b, v148
	v_mul_f32_e32 v165, 0xbfb8aa3b, v149
	v_mul_f32_e32 v166, 0xbfb8aa3b, v150
	v_mul_f32_e32 v167, 0xbfb8aa3b, v151
	v_mul_f32_e32 v168, 0xbfb8aa3b, v152
	v_mul_f32_e32 v169, 0xbfb8aa3b, v153
	v_exp_f32_e32 v162, v162
	v_exp_f32_e32 v163, v163
	v_exp_f32_e32 v164, v164
	v_exp_f32_e32 v165, v165
	v_exp_f32_e32 v166, v166
	v_exp_f32_e32 v167, v167
	v_exp_f32_e32 v168, v168
	v_exp_f32_e32 v169, v169
	v_add_f32_e32 v162, 1.0, v162
	v_add_f32_e32 v163, 1.0, v163
	v_add_f32_e32 v164, 1.0, v164
	v_add_f32_e32 v165, 1.0, v165
	v_add_f32_e32 v166, 1.0, v166
	v_add_f32_e32 v167, 1.0, v167
	v_add_f32_e32 v168, 1.0, v168
	v_add_f32_e32 v169, 1.0, v169
	v_rcp_f32_e32 v162, v162
	v_rcp_f32_e32 v163, v163
	v_rcp_f32_e32 v164, v164
	v_rcp_f32_e32 v165, v165
	v_rcp_f32_e32 v166, v166
	v_rcp_f32_e32 v167, v167
	v_rcp_f32_e32 v168, v168
	v_rcp_f32_e32 v169, v169
	s_nop 0
	v_pk_mul_f32 v[146:147], v[146:147], v[162:163]
	v_pk_mul_f32 v[148:149], v[148:149], v[164:165]
	v_pk_mul_f32 v[150:151], v[150:151], v[166:167]
	v_pk_mul_f32 v[152:153], v[152:153], v[168:169]
	v_pk_mul_f32 v[146:147], v[154:155], v[146:147]
	v_pk_mul_f32 v[148:149], v[156:157], v[148:149]
	v_pk_mul_f32 v[150:151], v[158:159], v[150:151]
	v_pk_mul_f32 v[152:153], v[160:161], v[152:153]
	v_cvt_pk_bf16_f32 v162, v146, v147
	v_cvt_pk_bf16_f32 v163, v148, v149
	v_cvt_pk_bf16_f32 v164, v150, v151
	v_cvt_pk_bf16_f32 v165, v152, v153
	global_store_dwordx4 v173, v[162:165], s[20:21]
	v_add_u32_e32 v173, 0x5600, v173
	s_waitcnt vmcnt(10)
	v_lshlrev_b32_e32 v114, 16, v82
	v_and_b32_e32 v115, 0xffff0000, v82
	v_lshlrev_b32_e32 v116, 16, v83
	v_and_b32_e32 v117, 0xffff0000, v83
	v_lshlrev_b32_e32 v118, 16, v84
	v_and_b32_e32 v119, 0xffff0000, v84
	v_lshlrev_b32_e32 v120, 16, v85
	v_and_b32_e32 v121, 0xffff0000, v85
	v_lshlrev_b32_e32 v122, 16, v86
	v_and_b32_e32 v123, 0xffff0000, v86
	v_lshlrev_b32_e32 v124, 16, v87
	v_and_b32_e32 v125, 0xffff0000, v87
	v_lshlrev_b32_e32 v126, 16, v88
	v_and_b32_e32 v127, 0xffff0000, v88
	v_lshlrev_b32_e32 v128, 16, v89
	v_and_b32_e32 v129, 0xffff0000, v89
	global_load_dwordx4 v[82:85], v172, s[16:17] nt
	global_load_dwordx4 v[86:89], v172, s[18:19] nt
	v_add_u32_e32 v172, 0xac00, v172
	v_pk_fma_f32 v[146:147], v[2:3], v[130:131], v[50:51]
	v_pk_fma_f32 v[148:149], v[4:5], v[132:133], v[52:53]
	v_pk_fma_f32 v[150:151], v[6:7], v[134:135], v[54:55]
	v_pk_fma_f32 v[152:153], v[8:9], v[136:137], v[56:57]
	v_pk_fma_f32 v[154:155], v[26:27], v[138:139], v[58:59]
	v_pk_fma_f32 v[156:157], v[28:29], v[140:141], v[60:61]
	v_pk_fma_f32 v[158:159], v[30:31], v[142:143], v[62:63]
	v_pk_fma_f32 v[160:161], v[32:33], v[144:145], v[64:65]
	v_pk_fma_f32 v[146:147], v[10:11], v[98:99], v[146:147]
	v_pk_fma_f32 v[148:149], v[12:13], v[100:101], v[148:149]
	v_pk_fma_f32 v[150:151], v[14:15], v[102:103], v[150:151]
	v_pk_fma_f32 v[152:153], v[16:17], v[104:105], v[152:153]
	v_pk_fma_f32 v[154:155], v[34:35], v[106:107], v[154:155]
	v_pk_fma_f32 v[156:157], v[36:37], v[108:109], v[156:157]
	v_pk_fma_f32 v[158:159], v[38:39], v[110:111], v[158:159]
	v_pk_fma_f32 v[160:161], v[40:41], v[112:113], v[160:161]
	v_pk_fma_f32 v[146:147], v[18:19], v[114:115], v[146:147]
	v_pk_fma_f32 v[148:149], v[20:21], v[116:117], v[148:149]
	v_pk_fma_f32 v[150:151], v[22:23], v[118:119], v[150:151]
	v_pk_fma_f32 v[152:153], v[24:25], v[120:121], v[152:153]
	v_pk_fma_f32 v[154:155], v[42:43], v[122:123], v[154:155]
	v_pk_fma_f32 v[156:157], v[44:45], v[124:125], v[156:157]
	v_pk_fma_f32 v[158:159], v[46:47], v[126:127], v[158:159]
	v_pk_fma_f32 v[160:161], v[48:49], v[128:129], v[160:161]
	v_mul_f32_e32 v162, 0xbfb8aa3b, v146
	v_mul_f32_e32 v163, 0xbfb8aa3b, v147
	v_mul_f32_e32 v164, 0xbfb8aa3b, v148
	v_mul_f32_e32 v165, 0xbfb8aa3b, v149
	v_mul_f32_e32 v166, 0xbfb8aa3b, v150
	v_mul_f32_e32 v167, 0xbfb8aa3b, v151
	v_mul_f32_e32 v168, 0xbfb8aa3b, v152
	v_mul_f32_e32 v169, 0xbfb8aa3b, v153
	v_exp_f32_e32 v162, v162
	v_exp_f32_e32 v163, v163
	v_exp_f32_e32 v164, v164
	v_exp_f32_e32 v165, v165
	v_exp_f32_e32 v166, v166
	v_exp_f32_e32 v167, v167
	v_exp_f32_e32 v168, v168
	v_exp_f32_e32 v169, v169
	v_add_f32_e32 v162, 1.0, v162
	v_add_f32_e32 v163, 1.0, v163
	v_add_f32_e32 v164, 1.0, v164
	v_add_f32_e32 v165, 1.0, v165
	v_add_f32_e32 v166, 1.0, v166
	v_add_f32_e32 v167, 1.0, v167
	v_add_f32_e32 v168, 1.0, v168
	v_add_f32_e32 v169, 1.0, v169
	v_rcp_f32_e32 v162, v162
	v_rcp_f32_e32 v163, v163
	v_rcp_f32_e32 v164, v164
	v_rcp_f32_e32 v165, v165
	v_rcp_f32_e32 v166, v166
	v_rcp_f32_e32 v167, v167
	v_rcp_f32_e32 v168, v168
	v_rcp_f32_e32 v169, v169
	s_nop 0
	v_pk_mul_f32 v[146:147], v[146:147], v[162:163]
	v_pk_mul_f32 v[148:149], v[148:149], v[164:165]
	v_pk_mul_f32 v[150:151], v[150:151], v[166:167]
	v_pk_mul_f32 v[152:153], v[152:153], v[168:169]
	v_pk_mul_f32 v[146:147], v[154:155], v[146:147]
	v_pk_mul_f32 v[148:149], v[156:157], v[148:149]
	v_pk_mul_f32 v[150:151], v[158:159], v[150:151]
	v_pk_mul_f32 v[152:153], v[160:161], v[152:153]
	v_cvt_pk_bf16_f32 v162, v146, v147
	v_cvt_pk_bf16_f32 v163, v148, v149
	v_cvt_pk_bf16_f32 v164, v150, v151
	v_cvt_pk_bf16_f32 v165, v152, v153
	global_store_dwordx4 v173, v[162:165], s[20:21]
	v_add_u32_e32 v173, 0x5600, v173
	s_waitcnt vmcnt(10)
	v_lshlrev_b32_e32 v130, 16, v90
	v_and_b32_e32 v131, 0xffff0000, v90
	v_lshlrev_b32_e32 v132, 16, v91
	v_and_b32_e32 v133, 0xffff0000, v91
	v_lshlrev_b32_e32 v134, 16, v92
	v_and_b32_e32 v135, 0xffff0000, v92
	v_lshlrev_b32_e32 v136, 16, v93
	v_and_b32_e32 v137, 0xffff0000, v93
	v_lshlrev_b32_e32 v138, 16, v94
	v_and_b32_e32 v139, 0xffff0000, v94
	v_lshlrev_b32_e32 v140, 16, v95
	v_and_b32_e32 v141, 0xffff0000, v95
	v_lshlrev_b32_e32 v142, 16, v96
	v_and_b32_e32 v143, 0xffff0000, v96
	v_lshlrev_b32_e32 v144, 16, v97
	v_and_b32_e32 v145, 0xffff0000, v97
	global_load_dwordx4 v[90:93], v172, s[16:17] nt
	global_load_dwordx4 v[94:97], v172, s[18:19] nt
	v_add_u32_e32 v172, 0xac00, v172
	v_pk_fma_f32 v[146:147], v[2:3], v[98:99], v[50:51]
	v_pk_fma_f32 v[148:149], v[4:5], v[100:101], v[52:53]
	v_pk_fma_f32 v[150:151], v[6:7], v[102:103], v[54:55]
	v_pk_fma_f32 v[152:153], v[8:9], v[104:105], v[56:57]
	v_pk_fma_f32 v[154:155], v[26:27], v[106:107], v[58:59]
	v_pk_fma_f32 v[156:157], v[28:29], v[108:109], v[60:61]
	v_pk_fma_f32 v[158:159], v[30:31], v[110:111], v[62:63]
	v_pk_fma_f32 v[160:161], v[32:33], v[112:113], v[64:65]
	v_pk_fma_f32 v[146:147], v[10:11], v[114:115], v[146:147]
	v_pk_fma_f32 v[148:149], v[12:13], v[116:117], v[148:149]
	v_pk_fma_f32 v[150:151], v[14:15], v[118:119], v[150:151]
	v_pk_fma_f32 v[152:153], v[16:17], v[120:121], v[152:153]
	v_pk_fma_f32 v[154:155], v[34:35], v[122:123], v[154:155]
	v_pk_fma_f32 v[156:157], v[36:37], v[124:125], v[156:157]
	v_pk_fma_f32 v[158:159], v[38:39], v[126:127], v[158:159]
	v_pk_fma_f32 v[160:161], v[40:41], v[128:129], v[160:161]
	v_pk_fma_f32 v[146:147], v[18:19], v[130:131], v[146:147]
	v_pk_fma_f32 v[148:149], v[20:21], v[132:133], v[148:149]
	v_pk_fma_f32 v[150:151], v[22:23], v[134:135], v[150:151]
	v_pk_fma_f32 v[152:153], v[24:25], v[136:137], v[152:153]
	v_pk_fma_f32 v[154:155], v[42:43], v[138:139], v[154:155]
	v_pk_fma_f32 v[156:157], v[44:45], v[140:141], v[156:157]
	v_pk_fma_f32 v[158:159], v[46:47], v[142:143], v[158:159]
	v_pk_fma_f32 v[160:161], v[48:49], v[144:145], v[160:161]
	v_mul_f32_e32 v162, 0xbfb8aa3b, v146
	v_mul_f32_e32 v163, 0xbfb8aa3b, v147
	v_mul_f32_e32 v164, 0xbfb8aa3b, v148
	v_mul_f32_e32 v165, 0xbfb8aa3b, v149
	v_mul_f32_e32 v166, 0xbfb8aa3b, v150
	v_mul_f32_e32 v167, 0xbfb8aa3b, v151
	v_mul_f32_e32 v168, 0xbfb8aa3b, v152
	v_mul_f32_e32 v169, 0xbfb8aa3b, v153
	v_exp_f32_e32 v162, v162
	v_exp_f32_e32 v163, v163
	v_exp_f32_e32 v164, v164
	v_exp_f32_e32 v165, v165
	v_exp_f32_e32 v166, v166
	v_exp_f32_e32 v167, v167
	v_exp_f32_e32 v168, v168
	v_exp_f32_e32 v169, v169
	v_add_f32_e32 v162, 1.0, v162
	v_add_f32_e32 v163, 1.0, v163
	v_add_f32_e32 v164, 1.0, v164
	v_add_f32_e32 v165, 1.0, v165
	v_add_f32_e32 v166, 1.0, v166
	v_add_f32_e32 v167, 1.0, v167
	v_add_f32_e32 v168, 1.0, v168
	v_add_f32_e32 v169, 1.0, v169
	v_rcp_f32_e32 v162, v162
	v_rcp_f32_e32 v163, v163
	v_rcp_f32_e32 v164, v164
	v_rcp_f32_e32 v165, v165
	v_rcp_f32_e32 v166, v166
	v_rcp_f32_e32 v167, v167
	v_rcp_f32_e32 v168, v168
	v_rcp_f32_e32 v169, v169
	s_nop 0
	v_pk_mul_f32 v[146:147], v[146:147], v[162:163]
	v_pk_mul_f32 v[148:149], v[148:149], v[164:165]
	v_pk_mul_f32 v[150:151], v[150:151], v[166:167]
	v_pk_mul_f32 v[152:153], v[152:153], v[168:169]
	v_pk_mul_f32 v[146:147], v[154:155], v[146:147]
	v_pk_mul_f32 v[148:149], v[156:157], v[148:149]
	v_pk_mul_f32 v[150:151], v[158:159], v[150:151]
	v_pk_mul_f32 v[152:153], v[160:161], v[152:153]
	v_cvt_pk_bf16_f32 v162, v146, v147
	v_cvt_pk_bf16_f32 v163, v148, v149
	v_cvt_pk_bf16_f32 v164, v150, v151
	v_cvt_pk_bf16_f32 v165, v152, v153
	global_store_dwordx4 v173, v[162:165], s[20:21]
	v_add_u32_e32 v173, 0x5600, v173
	s_waitcnt vmcnt(10)
	v_lshlrev_b32_e32 v98, 16, v66
	v_and_b32_e32 v99, 0xffff0000, v66
	v_lshlrev_b32_e32 v100, 16, v67
	v_and_b32_e32 v101, 0xffff0000, v67
	v_lshlrev_b32_e32 v102, 16, v68
	v_and_b32_e32 v103, 0xffff0000, v68
	v_lshlrev_b32_e32 v104, 16, v69
	v_and_b32_e32 v105, 0xffff0000, v69
	v_lshlrev_b32_e32 v106, 16, v70
	v_and_b32_e32 v107, 0xffff0000, v70
	v_lshlrev_b32_e32 v108, 16, v71
	v_and_b32_e32 v109, 0xffff0000, v71
	v_lshlrev_b32_e32 v110, 16, v72
	v_and_b32_e32 v111, 0xffff0000, v72
	v_lshlrev_b32_e32 v112, 16, v73
	v_and_b32_e32 v113, 0xffff0000, v73
	global_load_dwordx4 v[66:69], v172, s[16:17] nt
	global_load_dwordx4 v[70:73], v172, s[18:19] nt
	v_add_u32_e32 v172, 0xac00, v172
	v_pk_fma_f32 v[146:147], v[2:3], v[114:115], v[50:51]
	v_pk_fma_f32 v[148:149], v[4:5], v[116:117], v[52:53]
	v_pk_fma_f32 v[150:151], v[6:7], v[118:119], v[54:55]
	v_pk_fma_f32 v[152:153], v[8:9], v[120:121], v[56:57]
	v_pk_fma_f32 v[154:155], v[26:27], v[122:123], v[58:59]
	v_pk_fma_f32 v[156:157], v[28:29], v[124:125], v[60:61]
	v_pk_fma_f32 v[158:159], v[30:31], v[126:127], v[62:63]
	v_pk_fma_f32 v[160:161], v[32:33], v[128:129], v[64:65]
	v_pk_fma_f32 v[146:147], v[10:11], v[130:131], v[146:147]
	v_pk_fma_f32 v[148:149], v[12:13], v[132:133], v[148:149]
	v_pk_fma_f32 v[150:151], v[14:15], v[134:135], v[150:151]
	v_pk_fma_f32 v[152:153], v[16:17], v[136:137], v[152:153]
	v_pk_fma_f32 v[154:155], v[34:35], v[138:139], v[154:155]
	v_pk_fma_f32 v[156:157], v[36:37], v[140:141], v[156:157]
	v_pk_fma_f32 v[158:159], v[38:39], v[142:143], v[158:159]
	v_pk_fma_f32 v[160:161], v[40:41], v[144:145], v[160:161]
	v_pk_fma_f32 v[146:147], v[18:19], v[98:99], v[146:147]
	v_pk_fma_f32 v[148:149], v[20:21], v[100:101], v[148:149]
	v_pk_fma_f32 v[150:151], v[22:23], v[102:103], v[150:151]
	v_pk_fma_f32 v[152:153], v[24:25], v[104:105], v[152:153]
	v_pk_fma_f32 v[154:155], v[42:43], v[106:107], v[154:155]
	v_pk_fma_f32 v[156:157], v[44:45], v[108:109], v[156:157]
	v_pk_fma_f32 v[158:159], v[46:47], v[110:111], v[158:159]
	v_pk_fma_f32 v[160:161], v[48:49], v[112:113], v[160:161]
	v_mul_f32_e32 v162, 0xbfb8aa3b, v146
	v_mul_f32_e32 v163, 0xbfb8aa3b, v147
	v_mul_f32_e32 v164, 0xbfb8aa3b, v148
	v_mul_f32_e32 v165, 0xbfb8aa3b, v149
	v_mul_f32_e32 v166, 0xbfb8aa3b, v150
	v_mul_f32_e32 v167, 0xbfb8aa3b, v151
	v_mul_f32_e32 v168, 0xbfb8aa3b, v152
	v_mul_f32_e32 v169, 0xbfb8aa3b, v153
	v_exp_f32_e32 v162, v162
	v_exp_f32_e32 v163, v163
	v_exp_f32_e32 v164, v164
	v_exp_f32_e32 v165, v165
	v_exp_f32_e32 v166, v166
	v_exp_f32_e32 v167, v167
	v_exp_f32_e32 v168, v168
	v_exp_f32_e32 v169, v169
	v_add_f32_e32 v162, 1.0, v162
	v_add_f32_e32 v163, 1.0, v163
	v_add_f32_e32 v164, 1.0, v164
	v_add_f32_e32 v165, 1.0, v165
	v_add_f32_e32 v166, 1.0, v166
	v_add_f32_e32 v167, 1.0, v167
	v_add_f32_e32 v168, 1.0, v168
	v_add_f32_e32 v169, 1.0, v169
	v_rcp_f32_e32 v162, v162
	v_rcp_f32_e32 v163, v163
	v_rcp_f32_e32 v164, v164
	v_rcp_f32_e32 v165, v165
	v_rcp_f32_e32 v166, v166
	v_rcp_f32_e32 v167, v167
	v_rcp_f32_e32 v168, v168
	v_rcp_f32_e32 v169, v169
	s_nop 0
	v_pk_mul_f32 v[146:147], v[146:147], v[162:163]
	v_pk_mul_f32 v[148:149], v[148:149], v[164:165]
	v_pk_mul_f32 v[150:151], v[150:151], v[166:167]
	v_pk_mul_f32 v[152:153], v[152:153], v[168:169]
	v_pk_mul_f32 v[146:147], v[154:155], v[146:147]
	v_pk_mul_f32 v[148:149], v[156:157], v[148:149]
	v_pk_mul_f32 v[150:151], v[158:159], v[150:151]
	v_pk_mul_f32 v[152:153], v[160:161], v[152:153]
	v_cvt_pk_bf16_f32 v162, v146, v147
	v_cvt_pk_bf16_f32 v163, v148, v149
	v_cvt_pk_bf16_f32 v164, v150, v151
	v_cvt_pk_bf16_f32 v165, v152, v153
	global_store_dwordx4 v173, v[162:165], s[20:21]
	v_add_u32_e32 v173, 0x5600, v173
	s_waitcnt vmcnt(10)
	v_lshlrev_b32_e32 v114, 16, v74
	v_and_b32_e32 v115, 0xffff0000, v74
	v_lshlrev_b32_e32 v116, 16, v75
	v_and_b32_e32 v117, 0xffff0000, v75
	v_lshlrev_b32_e32 v118, 16, v76
	v_and_b32_e32 v119, 0xffff0000, v76
	v_lshlrev_b32_e32 v120, 16, v77
	v_and_b32_e32 v121, 0xffff0000, v77
	v_lshlrev_b32_e32 v122, 16, v78
	v_and_b32_e32 v123, 0xffff0000, v78
	v_lshlrev_b32_e32 v124, 16, v79
	v_and_b32_e32 v125, 0xffff0000, v79
	v_lshlrev_b32_e32 v126, 16, v80
	v_and_b32_e32 v127, 0xffff0000, v80
	v_lshlrev_b32_e32 v128, 16, v81
	v_and_b32_e32 v129, 0xffff0000, v81
	global_load_dwordx4 v[74:77], v172, s[16:17] nt
	global_load_dwordx4 v[78:81], v172, s[18:19] nt
	v_add_u32_e32 v172, 0xac00, v172
	v_pk_fma_f32 v[146:147], v[2:3], v[130:131], v[50:51]
	v_pk_fma_f32 v[148:149], v[4:5], v[132:133], v[52:53]
	v_pk_fma_f32 v[150:151], v[6:7], v[134:135], v[54:55]
	v_pk_fma_f32 v[152:153], v[8:9], v[136:137], v[56:57]
	v_pk_fma_f32 v[154:155], v[26:27], v[138:139], v[58:59]
	v_pk_fma_f32 v[156:157], v[28:29], v[140:141], v[60:61]
	v_pk_fma_f32 v[158:159], v[30:31], v[142:143], v[62:63]
	v_pk_fma_f32 v[160:161], v[32:33], v[144:145], v[64:65]
	v_pk_fma_f32 v[146:147], v[10:11], v[98:99], v[146:147]
	v_pk_fma_f32 v[148:149], v[12:13], v[100:101], v[148:149]
	v_pk_fma_f32 v[150:151], v[14:15], v[102:103], v[150:151]
	v_pk_fma_f32 v[152:153], v[16:17], v[104:105], v[152:153]
	v_pk_fma_f32 v[154:155], v[34:35], v[106:107], v[154:155]
	v_pk_fma_f32 v[156:157], v[36:37], v[108:109], v[156:157]
	v_pk_fma_f32 v[158:159], v[38:39], v[110:111], v[158:159]
	v_pk_fma_f32 v[160:161], v[40:41], v[112:113], v[160:161]
	v_pk_fma_f32 v[146:147], v[18:19], v[114:115], v[146:147]
	v_pk_fma_f32 v[148:149], v[20:21], v[116:117], v[148:149]
	v_pk_fma_f32 v[150:151], v[22:23], v[118:119], v[150:151]
	v_pk_fma_f32 v[152:153], v[24:25], v[120:121], v[152:153]
	v_pk_fma_f32 v[154:155], v[42:43], v[122:123], v[154:155]
	v_pk_fma_f32 v[156:157], v[44:45], v[124:125], v[156:157]
	v_pk_fma_f32 v[158:159], v[46:47], v[126:127], v[158:159]
	v_pk_fma_f32 v[160:161], v[48:49], v[128:129], v[160:161]
	v_mul_f32_e32 v162, 0xbfb8aa3b, v146
	v_mul_f32_e32 v163, 0xbfb8aa3b, v147
	v_mul_f32_e32 v164, 0xbfb8aa3b, v148
	v_mul_f32_e32 v165, 0xbfb8aa3b, v149
	v_mul_f32_e32 v166, 0xbfb8aa3b, v150
	v_mul_f32_e32 v167, 0xbfb8aa3b, v151
	v_mul_f32_e32 v168, 0xbfb8aa3b, v152
	v_mul_f32_e32 v169, 0xbfb8aa3b, v153
	v_exp_f32_e32 v162, v162
	v_exp_f32_e32 v163, v163
	v_exp_f32_e32 v164, v164
	v_exp_f32_e32 v165, v165
	v_exp_f32_e32 v166, v166
	v_exp_f32_e32 v167, v167
	v_exp_f32_e32 v168, v168
	v_exp_f32_e32 v169, v169
	v_add_f32_e32 v162, 1.0, v162
	v_add_f32_e32 v163, 1.0, v163
	v_add_f32_e32 v164, 1.0, v164
	v_add_f32_e32 v165, 1.0, v165
	v_add_f32_e32 v166, 1.0, v166
	v_add_f32_e32 v167, 1.0, v167
	v_add_f32_e32 v168, 1.0, v168
	v_add_f32_e32 v169, 1.0, v169
	v_rcp_f32_e32 v162, v162
	v_rcp_f32_e32 v163, v163
	v_rcp_f32_e32 v164, v164
	v_rcp_f32_e32 v165, v165
	v_rcp_f32_e32 v166, v166
	v_rcp_f32_e32 v167, v167
	v_rcp_f32_e32 v168, v168
	v_rcp_f32_e32 v169, v169
	s_nop 0
	v_pk_mul_f32 v[146:147], v[146:147], v[162:163]
	v_pk_mul_f32 v[148:149], v[148:149], v[164:165]
	v_pk_mul_f32 v[150:151], v[150:151], v[166:167]
	v_pk_mul_f32 v[152:153], v[152:153], v[168:169]
	v_pk_mul_f32 v[146:147], v[154:155], v[146:147]
	v_pk_mul_f32 v[148:149], v[156:157], v[148:149]
	v_pk_mul_f32 v[150:151], v[158:159], v[150:151]
	v_pk_mul_f32 v[152:153], v[160:161], v[152:153]
	v_cvt_pk_bf16_f32 v162, v146, v147
	v_cvt_pk_bf16_f32 v163, v148, v149
	v_cvt_pk_bf16_f32 v164, v150, v151
	v_cvt_pk_bf16_f32 v165, v152, v153
	global_store_dwordx4 v173, v[162:165], s[20:21]
	v_add_u32_e32 v173, 0x5600, v173
	s_waitcnt vmcnt(10)
	v_lshlrev_b32_e32 v130, 16, v82
	v_and_b32_e32 v131, 0xffff0000, v82
	v_lshlrev_b32_e32 v132, 16, v83
	v_and_b32_e32 v133, 0xffff0000, v83
	v_lshlrev_b32_e32 v134, 16, v84
	v_and_b32_e32 v135, 0xffff0000, v84
	v_lshlrev_b32_e32 v136, 16, v85
	v_and_b32_e32 v137, 0xffff0000, v85
	v_lshlrev_b32_e32 v138, 16, v86
	v_and_b32_e32 v139, 0xffff0000, v86
	v_lshlrev_b32_e32 v140, 16, v87
	v_and_b32_e32 v141, 0xffff0000, v87
	v_lshlrev_b32_e32 v142, 16, v88
	v_and_b32_e32 v143, 0xffff0000, v88
	v_lshlrev_b32_e32 v144, 16, v89
	v_and_b32_e32 v145, 0xffff0000, v89
	global_load_dwordx4 v[82:85], v172, s[16:17] nt
	global_load_dwordx4 v[86:89], v172, s[18:19] nt
	v_add_u32_e32 v172, 0xac00, v172
	v_pk_fma_f32 v[146:147], v[2:3], v[98:99], v[50:51]
	v_pk_fma_f32 v[148:149], v[4:5], v[100:101], v[52:53]
	v_pk_fma_f32 v[150:151], v[6:7], v[102:103], v[54:55]
	v_pk_fma_f32 v[152:153], v[8:9], v[104:105], v[56:57]
	v_pk_fma_f32 v[154:155], v[26:27], v[106:107], v[58:59]
	v_pk_fma_f32 v[156:157], v[28:29], v[108:109], v[60:61]
	v_pk_fma_f32 v[158:159], v[30:31], v[110:111], v[62:63]
	v_pk_fma_f32 v[160:161], v[32:33], v[112:113], v[64:65]
	v_pk_fma_f32 v[146:147], v[10:11], v[114:115], v[146:147]
	v_pk_fma_f32 v[148:149], v[12:13], v[116:117], v[148:149]
	v_pk_fma_f32 v[150:151], v[14:15], v[118:119], v[150:151]
	v_pk_fma_f32 v[152:153], v[16:17], v[120:121], v[152:153]
	v_pk_fma_f32 v[154:155], v[34:35], v[122:123], v[154:155]
	v_pk_fma_f32 v[156:157], v[36:37], v[124:125], v[156:157]
	v_pk_fma_f32 v[158:159], v[38:39], v[126:127], v[158:159]
	v_pk_fma_f32 v[160:161], v[40:41], v[128:129], v[160:161]
	v_pk_fma_f32 v[146:147], v[18:19], v[130:131], v[146:147]
	v_pk_fma_f32 v[148:149], v[20:21], v[132:133], v[148:149]
	v_pk_fma_f32 v[150:151], v[22:23], v[134:135], v[150:151]
	v_pk_fma_f32 v[152:153], v[24:25], v[136:137], v[152:153]
	v_pk_fma_f32 v[154:155], v[42:43], v[138:139], v[154:155]
	v_pk_fma_f32 v[156:157], v[44:45], v[140:141], v[156:157]
	v_pk_fma_f32 v[158:159], v[46:47], v[142:143], v[158:159]
	v_pk_fma_f32 v[160:161], v[48:49], v[144:145], v[160:161]
	v_mul_f32_e32 v162, 0xbfb8aa3b, v146
	v_mul_f32_e32 v163, 0xbfb8aa3b, v147
	v_mul_f32_e32 v164, 0xbfb8aa3b, v148
	v_mul_f32_e32 v165, 0xbfb8aa3b, v149
	v_mul_f32_e32 v166, 0xbfb8aa3b, v150
	v_mul_f32_e32 v167, 0xbfb8aa3b, v151
	v_mul_f32_e32 v168, 0xbfb8aa3b, v152
	v_mul_f32_e32 v169, 0xbfb8aa3b, v153
	v_exp_f32_e32 v162, v162
	v_exp_f32_e32 v163, v163
	v_exp_f32_e32 v164, v164
	v_exp_f32_e32 v165, v165
	v_exp_f32_e32 v166, v166
	v_exp_f32_e32 v167, v167
	v_exp_f32_e32 v168, v168
	v_exp_f32_e32 v169, v169
	v_add_f32_e32 v162, 1.0, v162
	v_add_f32_e32 v163, 1.0, v163
	v_add_f32_e32 v164, 1.0, v164
	v_add_f32_e32 v165, 1.0, v165
	v_add_f32_e32 v166, 1.0, v166
	v_add_f32_e32 v167, 1.0, v167
	v_add_f32_e32 v168, 1.0, v168
	v_add_f32_e32 v169, 1.0, v169
	v_rcp_f32_e32 v162, v162
	v_rcp_f32_e32 v163, v163
	v_rcp_f32_e32 v164, v164
	v_rcp_f32_e32 v165, v165
	v_rcp_f32_e32 v166, v166
	v_rcp_f32_e32 v167, v167
	v_rcp_f32_e32 v168, v168
	v_rcp_f32_e32 v169, v169
	s_nop 0
	v_pk_mul_f32 v[146:147], v[146:147], v[162:163]
	v_pk_mul_f32 v[148:149], v[148:149], v[164:165]
	v_pk_mul_f32 v[150:151], v[150:151], v[166:167]
	v_pk_mul_f32 v[152:153], v[152:153], v[168:169]
	v_pk_mul_f32 v[146:147], v[154:155], v[146:147]
	v_pk_mul_f32 v[148:149], v[156:157], v[148:149]
	v_pk_mul_f32 v[150:151], v[158:159], v[150:151]
	v_pk_mul_f32 v[152:153], v[160:161], v[152:153]
	v_cvt_pk_bf16_f32 v162, v146, v147
	v_cvt_pk_bf16_f32 v163, v148, v149
	v_cvt_pk_bf16_f32 v164, v150, v151
	v_cvt_pk_bf16_f32 v165, v152, v153
	global_store_dwordx4 v173, v[162:165], s[20:21]
	v_add_u32_e32 v173, 0x5600, v173
	s_waitcnt vmcnt(10)
	v_lshlrev_b32_e32 v98, 16, v90
	v_and_b32_e32 v99, 0xffff0000, v90
	v_lshlrev_b32_e32 v100, 16, v91
	v_and_b32_e32 v101, 0xffff0000, v91
	v_lshlrev_b32_e32 v102, 16, v92
	v_and_b32_e32 v103, 0xffff0000, v92
	v_lshlrev_b32_e32 v104, 16, v93
	v_and_b32_e32 v105, 0xffff0000, v93
	v_lshlrev_b32_e32 v106, 16, v94
	v_and_b32_e32 v107, 0xffff0000, v94
	v_lshlrev_b32_e32 v108, 16, v95
	v_and_b32_e32 v109, 0xffff0000, v95
	v_lshlrev_b32_e32 v110, 16, v96
	v_and_b32_e32 v111, 0xffff0000, v96
	v_lshlrev_b32_e32 v112, 16, v97
	v_and_b32_e32 v113, 0xffff0000, v97
	global_load_dwordx4 v[90:93], v172, s[16:17] nt
	global_load_dwordx4 v[94:97], v172, s[18:19] nt
	v_add_u32_e32 v172, 0xac00, v172
	v_pk_fma_f32 v[146:147], v[2:3], v[114:115], v[50:51]
	v_pk_fma_f32 v[148:149], v[4:5], v[116:117], v[52:53]
	v_pk_fma_f32 v[150:151], v[6:7], v[118:119], v[54:55]
	v_pk_fma_f32 v[152:153], v[8:9], v[120:121], v[56:57]
	v_pk_fma_f32 v[154:155], v[26:27], v[122:123], v[58:59]
	v_pk_fma_f32 v[156:157], v[28:29], v[124:125], v[60:61]
	v_pk_fma_f32 v[158:159], v[30:31], v[126:127], v[62:63]
	v_pk_fma_f32 v[160:161], v[32:33], v[128:129], v[64:65]
	v_pk_fma_f32 v[146:147], v[10:11], v[130:131], v[146:147]
	v_pk_fma_f32 v[148:149], v[12:13], v[132:133], v[148:149]
	v_pk_fma_f32 v[150:151], v[14:15], v[134:135], v[150:151]
	v_pk_fma_f32 v[152:153], v[16:17], v[136:137], v[152:153]
	v_pk_fma_f32 v[154:155], v[34:35], v[138:139], v[154:155]
	v_pk_fma_f32 v[156:157], v[36:37], v[140:141], v[156:157]
	v_pk_fma_f32 v[158:159], v[38:39], v[142:143], v[158:159]
	v_pk_fma_f32 v[160:161], v[40:41], v[144:145], v[160:161]
	v_pk_fma_f32 v[146:147], v[18:19], v[98:99], v[146:147]
	v_pk_fma_f32 v[148:149], v[20:21], v[100:101], v[148:149]
	v_pk_fma_f32 v[150:151], v[22:23], v[102:103], v[150:151]
	v_pk_fma_f32 v[152:153], v[24:25], v[104:105], v[152:153]
	v_pk_fma_f32 v[154:155], v[42:43], v[106:107], v[154:155]
	v_pk_fma_f32 v[156:157], v[44:45], v[108:109], v[156:157]
	v_pk_fma_f32 v[158:159], v[46:47], v[110:111], v[158:159]
	v_pk_fma_f32 v[160:161], v[48:49], v[112:113], v[160:161]
	v_mul_f32_e32 v162, 0xbfb8aa3b, v146
	v_mul_f32_e32 v163, 0xbfb8aa3b, v147
	v_mul_f32_e32 v164, 0xbfb8aa3b, v148
	v_mul_f32_e32 v165, 0xbfb8aa3b, v149
	v_mul_f32_e32 v166, 0xbfb8aa3b, v150
	v_mul_f32_e32 v167, 0xbfb8aa3b, v151
	v_mul_f32_e32 v168, 0xbfb8aa3b, v152
	v_mul_f32_e32 v169, 0xbfb8aa3b, v153
	v_exp_f32_e32 v162, v162
	v_exp_f32_e32 v163, v163
	v_exp_f32_e32 v164, v164
	v_exp_f32_e32 v165, v165
	v_exp_f32_e32 v166, v166
	v_exp_f32_e32 v167, v167
	v_exp_f32_e32 v168, v168
	v_exp_f32_e32 v169, v169
	v_add_f32_e32 v162, 1.0, v162
	v_add_f32_e32 v163, 1.0, v163
	v_add_f32_e32 v164, 1.0, v164
	v_add_f32_e32 v165, 1.0, v165
	v_add_f32_e32 v166, 1.0, v166
	v_add_f32_e32 v167, 1.0, v167
	v_add_f32_e32 v168, 1.0, v168
	v_add_f32_e32 v169, 1.0, v169
	v_rcp_f32_e32 v162, v162
	v_rcp_f32_e32 v163, v163
	v_rcp_f32_e32 v164, v164
	v_rcp_f32_e32 v165, v165
	v_rcp_f32_e32 v166, v166
	v_rcp_f32_e32 v167, v167
	v_rcp_f32_e32 v168, v168
	v_rcp_f32_e32 v169, v169
	s_nop 0
	v_pk_mul_f32 v[146:147], v[146:147], v[162:163]
	v_pk_mul_f32 v[148:149], v[148:149], v[164:165]
	v_pk_mul_f32 v[150:151], v[150:151], v[166:167]
	v_pk_mul_f32 v[152:153], v[152:153], v[168:169]
	v_pk_mul_f32 v[146:147], v[154:155], v[146:147]
	v_pk_mul_f32 v[148:149], v[156:157], v[148:149]
	v_pk_mul_f32 v[150:151], v[158:159], v[150:151]
	v_pk_mul_f32 v[152:153], v[160:161], v[152:153]
	v_cvt_pk_bf16_f32 v162, v146, v147
	v_cvt_pk_bf16_f32 v163, v148, v149
	v_cvt_pk_bf16_f32 v164, v150, v151
	v_cvt_pk_bf16_f32 v165, v152, v153
	global_store_dwordx4 v173, v[162:165], s[20:21]
	v_add_u32_e32 v173, 0x5600, v173
	v_mov_b32_e32 v114, v98
	v_mov_b32_e32 v115, v99
	v_mov_b32_e32 v116, v100
	v_mov_b32_e32 v117, v101
	v_mov_b32_e32 v118, v102
	v_mov_b32_e32 v119, v103
	v_mov_b32_e32 v120, v104
	v_mov_b32_e32 v121, v105
	v_mov_b32_e32 v122, v106
	v_mov_b32_e32 v123, v107
	v_mov_b32_e32 v124, v108
	v_mov_b32_e32 v125, v109
	v_mov_b32_e32 v126, v110
	v_mov_b32_e32 v127, v111
	v_mov_b32_e32 v128, v112
	v_mov_b32_e32 v129, v113
	v_mov_b32_e32 v98, v130
	v_mov_b32_e32 v99, v131
	v_mov_b32_e32 v100, v132
	v_mov_b32_e32 v101, v133
	v_mov_b32_e32 v102, v134
	v_mov_b32_e32 v103, v135
	v_mov_b32_e32 v104, v136
	v_mov_b32_e32 v105, v137
	v_mov_b32_e32 v106, v138
	v_mov_b32_e32 v107, v139
	v_mov_b32_e32 v108, v140
	v_mov_b32_e32 v109, v141
	v_mov_b32_e32 v110, v142
	v_mov_b32_e32 v111, v143
	v_mov_b32_e32 v112, v144
	v_mov_b32_e32 v113, v145
	s_sub_u32 s22, s22, 1
	s_cmp_lg_u32 s22, 0
	s_cbranch_scc1 .Lgrp_cw0
	s_waitcnt vmcnt(0)
	v_lshrrev_b32_e32 v1, 6, v0
	v_lshlrev_b32_e32 v1, 14, v1
	v_and_b32_e32 v2, 63, v0
	v_lshl_or_b32 v1, v2, 4, v1
	ds_read_b128 v[138:141], v1
	ds_read_b128 v[142:145], v1 offset:1024
	ds_read_b128 v[146:149], v1 offset:2048
	ds_read_b128 v[150:153], v1 offset:3072
	ds_read_b128 v[154:157], v1 offset:4096
	ds_read_b128 v[158:161], v1 offset:5120
	ds_read_b128 v[162:165], v1 offset:6144
	ds_read_b128 v[166:169], v1 offset:7168
	ds_read_b128 v[170:173], v1 offset:8192
	ds_read_b128 v[174:177], v1 offset:9216
	ds_read_b128 v[178:181], v1 offset:10240
	ds_read_b128 v[182:185], v1 offset:11264
	ds_read_b128 v[186:189], v1 offset:12288
	ds_read_b128 v[190:193], v1 offset:13312
	ds_read_b128 v[194:197], v1 offset:14336
	ds_read_b128 v[198:201], v1 offset:15360
	s_waitcnt lgkmcnt(0)

.LBB0_1768:
	s_cmp_lt_i32 s62, 23
	s_cselect_b64 s[0:1], -1, 0
	s_and_b64 s[2:3], s[0:1], s[2:3]
	s_andn2_b64 vcc, exec, s[2:3]
	s_cbranch_vccnz .LBB0_1781
	s_lshl_b32 s6, s88, 9
	v_or_b32_e32 v1, s6, v0
	s_mov_b32 s2, 0x158000
	v_cmp_gt_i32_e32 vcc, s2, v1
	s_and_saveexec_b64 s[2:3], vcc
	s_cbranch_execz .LBB0_1780
	s_waitcnt vmcnt(0) lgkmcnt(0)
	v_lshrrev_b32_e32 v1, 6, v0
	v_lshlrev_b32_e32 v1, 14, v1
	v_and_b32_e32 v2, 63, v0
	v_lshl_or_b32 v1, v2, 4, v1
	ds_write_b128 v1, v[138:141]
	ds_write_b128 v1, v[142:145] offset:1024
	ds_write_b128 v1, v[146:149] offset:2048
	ds_write_b128 v1, v[150:153] offset:3072
	ds_write_b128 v1, v[154:157] offset:4096
	ds_write_b128 v1, v[158:161] offset:5120
	ds_write_b128 v1, v[162:165] offset:6144
	ds_write_b128 v1, v[166:169] offset:7168
	ds_write_b128 v1, v[170:173] offset:8192
	ds_write_b128 v1, v[174:177] offset:9216
	ds_write_b128 v1, v[178:181] offset:10240
	ds_write_b128 v1, v[182:185] offset:11264
	ds_write_b128 v1, v[186:189] offset:12288
	ds_write_b128 v1, v[190:193] offset:13312
	ds_write_b128 v1, v[194:197] offset:14336
	ds_write_b128 v1, v[198:201] offset:15360
	v_readlane_b32 s24, v247, 3
	v_readlane_b32 s25, v247, 4
	s_load_dwordx4 s[8:11], s[24:25], 0xd0
	s_waitcnt lgkmcnt(0)
	s_add_u32 s12, s10, 0x15800
	s_addc_u32 s13, s11, 0
	s_add_u32 s14, s12, 0xac00
	s_addc_u32 s15, s13, 0
	s_add_u32 s8, s8, 0x40800
	s_addc_u32 s9, s9, 0
	s_add_u32 s10, s8, 0xac00
	s_addc_u32 s11, s9, 0
	s_mov_b64 s[16:17], s[70:71]
	s_add_u32 s18, s70, 0x5600
	s_addc_u32 s19, s71, 0
	s_add_u32 s20, s94, 0x72500000
	s_addc_u32 s21, s95, 0
	s_mov_b32 s23, 0x56000
	s_mov_b32 s28, 0x2b000
	s_mov_b32 s22, 11
	s_lshl_b32 s24, s88, 9
	v_add_u32_e32 v1, s24, v0
	v_lshrrev_b32_e32 v175, 5, v1
	v_mov_b32_e32 v178, 0xbe83
	v_mul_lo_u32 v175, v175, v178
	v_lshrrev_b32_e32 v175, 21, v175
	v_mul_u32_u24_e32 v178, 0x560, v175
	v_sub_u32_e32 v170, v1, v178
	v_min_u32_e32 v175, 94, v175
	v_mul_u32_u24_e32 v175, 0xac7, v175
	v_lshrrev_b32_e32 v171, 8, v175
	v_lshlrev_b32_e32 v175, 4, v170
	v_mad_u32_u24 v172, v171, s23, v175
	v_mad_u32_u24 v173, v171, s28, v175
	v_lshlrev_b32_e32 v174, 5, v170
	v_add_u32_e32 v176, 0x15800, v174
	v_add_u32_e32 v177, 0x2b000, v174
	global_load_dwordx4 v[2:5], v174, s[8:9]
	global_load_dwordx4 v[6:9], v174, s[8:9] offset:16
	global_load_dwordx4 v[10:13], v176, s[8:9]
	global_load_dwordx4 v[14:17], v176, s[8:9] offset:16
	global_load_dwordx4 v[18:21], v177, s[8:9]
	global_load_dwordx4 v[22:25], v177, s[8:9] offset:16
	global_load_dwordx4 v[50:53], v174, s[12:13]
	global_load_dwordx4 v[54:57], v174, s[12:13] offset:16
	global_load_dwordx4 v[26:29], v174, s[10:11]
	global_load_dwordx4 v[30:33], v174, s[10:11] offset:16
	global_load_dwordx4 v[34:37], v176, s[10:11]
	global_load_dwordx4 v[38:41], v176, s[10:11] offset:16
	global_load_dwordx4 v[42:45], v177, s[10:11]
	global_load_dwordx4 v[46:49], v177, s[10:11] offset:16
	global_load_dwordx4 v[58:61], v174, s[14:15]
	global_load_dwordx4 v[62:65], v174, s[14:15] offset:16
	v_and_b32_e32 v175, 0xff, v171
	v_cmp_ne_u32_e32 vcc, 0, v175
	v_mov_b32_e32 v178, 0x15800
	s_nop 0
	v_cndmask_b32_e32 v175, 0, v178, vcc
	v_sub_u32_e32 v176, v172, v175
	v_lshrrev_b32_e32 v175, 1, v175
	v_sub_u32_e32 v177, v172, v175
	global_load_dwordx4 v[66:69], v176, s[16:17] nt
	global_load_dwordx4 v[70:73], v176, s[18:19] nt
	global_load_dwordx4 v[74:77], v177, s[16:17] nt
	global_load_dwordx4 v[78:81], v177, s[18:19] nt
	s_waitcnt vmcnt(0)
	v_lshlrev_b32_e32 v98, 16, v66
	v_and_b32_e32 v99, 0xffff0000, v66
	v_lshlrev_b32_e32 v100, 16, v67
	v_and_b32_e32 v101, 0xffff0000, v67
	v_lshlrev_b32_e32 v102, 16, v68
	v_and_b32_e32 v103, 0xffff0000, v68
	v_lshlrev_b32_e32 v104, 16, v69
	v_and_b32_e32 v105, 0xffff0000, v69
	v_lshlrev_b32_e32 v106, 16, v70
	v_and_b32_e32 v107, 0xffff0000, v70
	v_lshlrev_b32_e32 v108, 16, v71
	v_and_b32_e32 v109, 0xffff0000, v71
	v_lshlrev_b32_e32 v110, 16, v72
	v_and_b32_e32 v111, 0xffff0000, v72
	v_lshlrev_b32_e32 v112, 16, v73
	v_and_b32_e32 v113, 0xffff0000, v73
	v_lshlrev_b32_e32 v114, 16, v74
	v_and_b32_e32 v115, 0xffff0000, v74
	v_lshlrev_b32_e32 v116, 16, v75
	v_and_b32_e32 v117, 0xffff0000, v75
	v_lshlrev_b32_e32 v118, 16, v76
	v_and_b32_e32 v119, 0xffff0000, v76
	v_lshlrev_b32_e32 v120, 16, v77
	v_and_b32_e32 v121, 0xffff0000, v77
	v_lshlrev_b32_e32 v122, 16, v78
	v_and_b32_e32 v123, 0xffff0000, v78
	v_lshlrev_b32_e32 v124, 16, v79
	v_and_b32_e32 v125, 0xffff0000, v79
	v_lshlrev_b32_e32 v126, 16, v80
	v_and_b32_e32 v127, 0xffff0000, v80
	v_lshlrev_b32_e32 v128, 16, v81
	v_and_b32_e32 v129, 0xffff0000, v81
	global_load_dwordx4 v[66:69], v172, s[16:17] nt
	global_load_dwordx4 v[70:73], v172, s[18:19] nt
	v_add_u32_e32 v172, 0xac00, v172
	global_load_dwordx4 v[74:77], v172, s[16:17] nt
	global_load_dwordx4 v[78:81], v172, s[18:19] nt
	v_add_u32_e32 v172, 0xac00, v172
	global_load_dwordx4 v[82:85], v172, s[16:17] nt
	global_load_dwordx4 v[86:89], v172, s[18:19] nt
	v_add_u32_e32 v172, 0xac00, v172
	global_load_dwordx4 v[90:93], v172, s[16:17] nt
	global_load_dwordx4 v[94:97], v172, s[18:19] nt
	v_add_u32_e32 v172, 0xac00, v172
	s_waitcnt vmcnt(0)
